# in-proj layer-1 XCD permutation variant: XCDs 6,7 take (T,K0,T) instead of (K0,T,T)
# baseline (speedup 1.0000x reference)
;     __device__ __forceinline__ bool idx(int i, int& Lp, int& half) const {
;         const int R = n / G, T = n % G; long L; half = 0;
;         if (i == R && T > 0 && 2 * T <= G) { if (c >= 2 * T) return false; L = (long)R * G + (c >> 1); half = 1 + (c & 1); }
;         else { L = (long)i * G + c; if (L >= n) return false; }
;         const int w = (int)L, q = n / 8, r = n % 8, xcd = w % 8, off = w / 8;
;         Lp = (xcd < r ? xcd * (q + 1) : r * (q + 1) + (xcd - r) * q) + off; return true;
;     __device__ __forceinline__ bool next(int i, Unit& u) const {
;     ...
;         if (!l1) { if (q < 504) { kind = 0; const int gid = q / 56, rem = q % 56; pm = gid * 8 + (rem & 7); pn = rem >> 3; } else if (q < 760) { const int s = q - 504; kind = 1; bt = s >> 5; pn = (s & 31) >> 2; pm = s & 3; } else { const int s = q - 760; kind = 2; bt = s >> 2; pm = s & 3; pn = 0; } }
;         else { if (q < 448) { kind = 0; const int gid = q / 56, rem = q % 56; pm = gid * 8 + (rem & 7); pn = rem >> 3; } else if (q < 488) { const int s = q - 448, r5 = s % 5; kind = 0; pm = 64 + s / 5; pn = r5 < 4 ? r5 + 1 : 6; }
;                else if (q < 744) { const int s = q - 488; kind = 1; bt = s >> 5; pn = (s & 31) >> 2; pm = s & 3; } else { const int s = q - 744; kind = 2; bt = s / 3; pm = 1 + s % 3; pn = 0; } }
.Lperm_hi_a:
	s_lshl_b32 s23, s20, 1
	s_lshr_b32 s18, s22, 1
	s_add_i32 s23, s23, s18
	s_add_i32 s23, s23, 8
	s_add_i32 s18, s20, 6
	s_cmp_eq_u32 s22, 1
	s_cselect_b32 s23, s18, s23

;     __device__ __forceinline__ bool idx(int i, int& Lp, int& half) const {
;         const int R = n / G, T = n % G; long L; half = 0;
;         if (i == R && T > 0 && 2 * T <= G) { if (c >= 2 * T) return false; L = (long)R * G + (c >> 1); half = 1 + (c & 1); }
;         else { L = (long)i * G + c; if (L >= n) return false; }
;         const int w = (int)L, q = n / 8, r = n % 8, xcd = w % 8, off = w / 8;
;         Lp = (xcd < r ? xcd * (q + 1) : r * (q + 1) + (xcd - r) * q) + off; return true;
;     __device__ __forceinline__ bool next(int i, Unit& u) const {
;     ...
;         if (!l1) { if (q < 504) { kind = 0; const int gid = q / 56, rem = q % 56; pm = gid * 8 + (rem & 7); pn = rem >> 3; } else if (q < 760) { const int s = q - 504; kind = 1; bt = s >> 5; pn = (s & 31) >> 2; pm = s & 3; } else { const int s = q - 760; kind = 2; bt = s >> 2; pm = s & 3; pn = 0; } }
;         else { if (q < 448) { kind = 0; const int gid = q / 56, rem = q % 56; pm = gid * 8 + (rem & 7); pn = rem >> 3; } else if (q < 488) { const int s = q - 448, r5 = s % 5; kind = 0; pm = 64 + s / 5; pn = r5 < 4 ? r5 + 1 : 6; }
;                else if (q < 744) { const int s = q - 488; kind = 1; bt = s >> 5; pn = (s & 31) >> 2; pm = s & 3; } else { const int s = q - 744; kind = 2; bt = s / 3; pm = 1 + s % 3; pn = 0; } }
.Lperm_hi_b:
	s_lshl_b32 s39, s28, 1
	s_lshr_b32 s8, s38, 1
	s_add_i32 s39, s39, s8
	s_add_i32 s39, s39, 8
	s_add_i32 s8, s28, 6
	s_cmp_eq_u32 s38, 1
	s_cselect_b32 s39, s8, s39
